# P0 x-copy queue: pull-ahead pop (next chunk's fetch-add issued before the current chunk's loads while chunk index <= 160; synchronous near the tail)
# baseline (speedup 1.0000x reference)
; #define LAS __attribute__((address_space(3)))
; __device__ __forceinline__ void p0_phase(const Args& a, LAS unsigned char* lds, int tid, int lane, int wave, int bid, int G) {
;     ...
;     {
;         unsigned* head = (unsigned*)(a.ws + WS_BAR) + QUEUE_WORD + 192;
;         volatile LAS unsigned* slot = (volatile LAS unsigned*)(lds + 131072 + 128);
;         bf16_t* XB0 = (bf16_t*)(a.ws + WS_XB0);
;         for (;;) {
;             if (threadIdx.x == 0) slot[0] = __hip_atomic_fetch_add(head, 1u, __ATOMIC_RELAXED, __HIP_MEMORY_SCOPE_AGENT);
;             __syncthreads();
;             const int q = (int)slot[0];
;             __syncthreads();
;             if (q >= M / 64) break;
.LBB0_123:
	s_mov_b32 s50, 0
	s_add_u32 s4, s78, 0x1703b00
	s_addc_u32 s5, s79, 0
	s_add_u32 s6, s78, 0xcc00000
	s_addc_u32 s7, s79, 0
	s_add_i32 s30, 0, 0x20080
	s_lshl_b32 s3, s3, 3
	s_mov_b32 s9, 0
	v_mov_b32_e32 v113, 0
	v_mov_b32_e32 v115, s30
	s_movk_i32 s31, 0x10f
	s_branch .LBB0_126

; __device__ __forceinline__ void p0_phase(const Args& a, LAS unsigned char* lds, int tid, int lane, int wave, int bid, int G) {
;     ...
;         for (;;) {
;             if (threadIdx.x == 0) slot[0] = __hip_atomic_fetch_add(head, 1u, __ATOMIC_RELAXED, __HIP_MEMORY_SCOPE_AGENT);
;             __syncthreads();
;             const int q = (int)slot[0];
;             __syncthreads();
;             if (q >= M / 64) break;
;             asm volatile("" : "+v"(tid)); lane = tid & 63;
;             f32x4 v[8][4];
; #pragma unroll
;             for (int r = 0; r < 8; ++r) { const int row = q * 64 + wave * 8 + r;
;                 const float* xrow = row < MP ? a.in[0] + (size_t)row * D : a.in[1] + (size_t)(row - MP) * D;
; #pragma unroll
;                 for (int j = 0; j < 4; ++j) v[r][j] = __builtin_nontemporal_load((const f32x4*)xrow + 64 * j + lane); }
.LBB0_126:
	s_mov_b64 s[0:1], exec
	v_readlane_b32 s10, v253, 2
	v_readlane_b32 s11, v253, 3
	s_and_b64 s[10:11], s[0:1], s[10:11]
	s_mov_b64 exec, s[10:11]
	s_cbranch_execz .LBB0_130
	s_cmp_lg_u32 s50, 0
	s_cbranch_scc1 .Lxq_have
	v_mov_b32_e32 v140, 1
	global_atomic_add v140, v113, v140, s[4:5] sc0
.Lxq_have:
	s_waitcnt vmcnt(0)
	v_mov_b32_e32 v1, s30
	ds_write_b32 v1, v140
.LBB0_130:
	s_or_b64 exec, exec, s[0:1]
	s_waitcnt lgkmcnt(0)
	s_barrier
	ds_read_b32 v0, v115
	s_waitcnt lgkmcnt(0)
	s_barrier
	v_cmp_lt_i32_e64 s[0:1], s31, v0
	v_readfirstlane_b32 s8, v0
	s_and_b64 vcc, exec, s[0:1]
	s_cbranch_vccnz .LBB0_125
	s_mov_b32 s50, 0
	s_cmpk_gt_i32 s8, 160
	s_cbranch_scc1 .Lxq_noip
	s_mov_b32 s50, 1
	s_mov_b64 s[12:13], exec
	v_readlane_b32 s10, v253, 2
	v_readlane_b32 s11, v253, 3
	s_and_b64 s[10:11], s[12:13], s[10:11]
	s_mov_b64 exec, s[10:11]
	s_cbranch_execz .Lxq_ipskip
	v_mov_b32_e32 v140, 1
	global_atomic_add v140, v113, v140, s[4:5] sc0
.Lxq_ipskip:
	s_mov_b64 exec, s[12:13]
.Lxq_noip:
	s_lshl_b32 s8, s8, 6
	s_add_i32 s22, s8, s3
	v_readlane_b32 s52, v253, 4
	s_add_i32 s8, s22, 0xffffc000
	s_ashr_i32 s23, s22, 31
	v_readlane_b32 s53, v253, 5
	s_cmpk_lt_i32 s22, 0x4000
	v_readlane_b32 s54, v253, 6
	v_readlane_b32 s55, v253, 7
	s_mov_b64 s[44:45], s[52:53]
	s_cselect_b32 s11, s23, 0
	s_cselect_b32 s10, s22, s8
	s_mov_b64 s[46:47], s[54:55]
	s_cselect_b32 s8, s45, s47
	s_cselect_b32 s12, s44, s46
	s_lshl_b64 s[10:11], s[10:11], 12
	s_add_u32 s10, s12, s10
	s_addc_u32 s11, s8, s11
	s_or_b32 s24, s22, 1
	s_ashr_i32 s25, s24, 31
	v_and_b32_e32 v112, 63, v114
	s_add_i32 s8, s22, 0xffffc001
	v_lshlrev_b32_e32 v116, 4, v112
	s_cmpk_lt_i32 s24, 0x4000
	global_load_dwordx4 v[108:111], v116, s[10:11] nt
	global_load_dwordx4 v[88:91], v116, s[10:11] offset:1024 nt
	global_load_dwordx4 v[60:63], v116, s[10:11] offset:2048 nt
	global_load_dwordx4 v[32:35], v116, s[10:11] offset:3072 nt
	s_cselect_b32 s11, s25, 0
	s_cselect_b32 s10, s24, s8
	s_cselect_b32 s8, s45, s47
	s_cselect_b32 s12, s44, s46
	s_lshl_b64 s[10:11], s[10:11], 12
	s_add_u32 s10, s12, s10
	s_addc_u32 s11, s8, s11
	s_or_b32 s20, s22, 2
	s_ashr_i32 s21, s20, 31
	s_add_i32 s8, s22, 0xffffc002
	s_cmpk_lt_i32 s20, 0x4000
	global_load_dwordx4 v[104:107], v116, s[10:11] nt
	global_load_dwordx4 v[76:79], v116, s[10:11] offset:1024 nt
	global_load_dwordx4 v[48:51], v116, s[10:11] offset:2048 nt
	global_load_dwordx4 v[20:23], v116, s[10:11] offset:3072 nt
	s_cselect_b32 s11, s21, 0
	s_cselect_b32 s10, s20, s8
	s_cselect_b32 s8, s45, s47
	s_cselect_b32 s12, s44, s46
	s_lshl_b64 s[10:11], s[10:11], 12
	s_add_u32 s10, s12, s10
	s_addc_u32 s11, s8, s11
	s_or_b32 s18, s22, 3
	s_ashr_i32 s19, s18, 31
	s_add_i32 s8, s22, 0xffffc003
	s_cmpk_lt_i32 s18, 0x4000
	global_load_dwordx4 v[100:103], v116, s[10:11] nt
	global_load_dwordx4 v[72:75], v116, s[10:11] offset:1024 nt
	global_load_dwordx4 v[44:47], v116, s[10:11] offset:2048 nt
	global_load_dwordx4 v[16:19], v116, s[10:11] offset:3072 nt
	s_cselect_b32 s11, s19, 0
	s_cselect_b32 s10, s18, s8
	s_cselect_b32 s8, s45, s47
	s_cselect_b32 s12, s44, s46
	s_lshl_b64 s[10:11], s[10:11], 12
	s_add_u32 s10, s12, s10
	s_addc_u32 s11, s8, s11
	s_or_b32 s16, s22, 4
	s_ashr_i32 s17, s16, 31
	s_add_i32 s8, s22, 0xffffc004
	s_cmpk_lt_i32 s16, 0x4000
	global_load_dwordx4 v[96:99], v116, s[10:11] nt
	global_load_dwordx4 v[68:71], v116, s[10:11] offset:1024 nt
	global_load_dwordx4 v[40:43], v116, s[10:11] offset:2048 nt
	global_load_dwordx4 v[12:15], v116, s[10:11] offset:3072 nt
	s_cselect_b32 s11, s17, 0
	s_cselect_b32 s10, s16, s8
	s_cselect_b32 s8, s45, s47
	s_cselect_b32 s12, s44, s46
	s_lshl_b64 s[10:11], s[10:11], 12
	s_add_u32 s10, s12, s10
	s_addc_u32 s11, s8, s11
	s_or_b32 s14, s22, 5
	s_ashr_i32 s15, s14, 31
	s_add_i32 s8, s22, 0xffffc005
	s_cmpk_lt_i32 s14, 0x4000
	global_load_dwordx4 v[92:95], v116, s[10:11] nt
	global_load_dwordx4 v[64:67], v116, s[10:11] offset:1024 nt
	global_load_dwordx4 v[36:39], v116, s[10:11] offset:2048 nt
	global_load_dwordx4 v[8:11], v116, s[10:11] offset:3072 nt
	s_cselect_b32 s11, s15, 0
	s_cselect_b32 s10, s14, s8
	s_cselect_b32 s8, s45, s47
	s_cselect_b32 s12, s44, s46
	s_lshl_b64 s[10:11], s[10:11], 12
	s_add_u32 s10, s12, s10
	s_addc_u32 s11, s8, s11
	s_or_b32 s12, s22, 6
	s_ashr_i32 s13, s12, 31
	s_add_i32 s8, s22, 0xffffc006
	s_cmpk_lt_i32 s12, 0x4000
	global_load_dwordx4 v[80:83], v116, s[10:11] nt
	global_load_dwordx4 v[52:55], v116, s[10:11] offset:1024 nt
	global_load_dwordx4 v[24:27], v116, s[10:11] offset:2048 nt
	global_load_dwordx4 v[0:3], v116, s[10:11] offset:3072 nt
	s_cselect_b32 s11, s13, 0
	s_cselect_b32 s10, s12, s8
	s_cselect_b32 s8, s45, s47
	s_cselect_b32 s26, s44, s46
	s_lshl_b64 s[10:11], s[10:11], 12
	s_add_u32 s10, s26, s10
	s_addc_u32 s11, s8, s11
	global_load_dwordx4 v[84:87], v116, s[10:11] nt
	global_load_dwordx4 v[56:59], v116, s[10:11] offset:1024 nt
	global_load_dwordx4 v[28:31], v116, s[10:11] offset:2048 nt
	global_load_dwordx4 v[4:7], v116, s[10:11] offset:3072 nt
	s_or_b32 s10, s22, 7
	s_cmpk_lt_i32 s10, 0x4000
	s_mov_b64 s[28:29], -1
	v_readlane_b32 s56, v253, 8
	v_readlane_b32 s57, v253, 9
	v_readlane_b32 s58, v253, 10
	v_readlane_b32 s59, v253, 11
	v_readlane_b32 s60, v253, 12
	v_readlane_b32 s61, v253, 13
	v_readlane_b32 s62, v253, 14
	v_readlane_b32 s63, v253, 15
	v_readlane_b32 s64, v253, 16
	v_readlane_b32 s65, v253, 17
	v_readlane_b32 s66, v253, 18
	v_readlane_b32 s67, v253, 19
	s_cbranch_scc1 .LBB0_133
	v_readlane_b32 s52, v253, 4
	v_readlane_b32 s53, v253, 5
	s_add_i32 s8, s22, 0xffffc007
	v_readlane_b32 s54, v253, 6
	v_readlane_b32 s55, v253, 7
	s_mov_b64 s[44:45], s[52:53]
	s_lshl_b64 s[26:27], s[8:9], 12
	s_mov_b64 s[46:47], s[54:55]
	s_add_u32 s26, s46, s26
	s_addc_u32 s27, s47, s27
	s_mov_b32 s11, s9
	s_mov_b64 s[28:29], 0
	v_readlane_b32 s56, v253, 8
	v_readlane_b32 s57, v253, 9
	v_readlane_b32 s58, v253, 10
	v_readlane_b32 s59, v253, 11
	v_readlane_b32 s60, v253, 12
	v_readlane_b32 s61, v253, 13
	v_readlane_b32 s62, v253, 14
	v_readlane_b32 s63, v253, 15
	v_readlane_b32 s64, v253, 16
	v_readlane_b32 s65, v253, 17
	v_readlane_b32 s66, v253, 18
	v_readlane_b32 s67, v253, 19
